# kalign:6 on p11pos+sel_ip: the eight GEMM K-loop heads aligned to 64 bytes
# baseline (speedup 1.0000x reference)
.LBB0_215:
	s_ashr_i32 s17, s16, 31
	s_lshl_b64 s[20:21], s[16:17], 19
	s_add_u32 s20, s30, s20
	s_addc_u32 s21, s31, s21
	s_and_b64 s[22:23], s[4:5], exec
	s_cselect_b32 s17, s21, s25
	s_cselect_b32 s47, s20, s24
	s_ashr_i32 s15, s14, 31
	s_lshl_b64 s[22:23], s[14:15], 19
	s_add_u32 s22, s92, s22
	s_addc_u32 s23, s93, s23
	s_and_b64 s[28:29], s[4:5], exec
	s_cselect_b32 s15, s23, s27
	s_cselect_b32 s48, s22, s26
	s_add_u32 s24, s24, 0x40080
	s_addc_u32 s25, s25, 0
	s_add_u32 s49, s26, 0x100
	v_mov_b32_e32 v0, 0
	s_addc_u32 s54, s27, 0
	s_mov_b32 s55, -2
	v_mov_b32_e32 v1, v0
	v_mov_b32_e32 v2, v0
	v_mov_b32_e32 v3, v0
	v_mov_b32_e32 v4, v0
	v_mov_b32_e32 v5, v0
	v_mov_b32_e32 v6, v0
	v_mov_b32_e32 v7, v0
	v_mov_b32_e32 v8, v0
	v_mov_b32_e32 v9, v0
	v_mov_b32_e32 v10, v0
	v_mov_b32_e32 v11, v0
	v_mov_b32_e32 v12, v0
	v_mov_b32_e32 v13, v0
	v_mov_b32_e32 v14, v0
	v_mov_b32_e32 v15, v0
	v_mov_b32_e32 v24, v0
	v_mov_b32_e32 v25, v0
	v_mov_b32_e32 v26, v0
	v_mov_b32_e32 v27, v0
	v_mov_b32_e32 v28, v0
	v_mov_b32_e32 v29, v0
	v_mov_b32_e32 v30, v0
	v_mov_b32_e32 v31, v0
	v_mov_b32_e32 v40, v0
	v_mov_b32_e32 v41, v0
	v_mov_b32_e32 v42, v0
	v_mov_b32_e32 v43, v0
	v_mov_b32_e32 v44, v0
	v_mov_b32_e32 v45, v0
	v_mov_b32_e32 v46, v0
	v_mov_b32_e32 v47, v0
	v_mov_b32_e32 v16, v0
	v_mov_b32_e32 v17, v0
	v_mov_b32_e32 v18, v0
	v_mov_b32_e32 v19, v0
	v_mov_b32_e32 v20, v0
	v_mov_b32_e32 v21, v0
	v_mov_b32_e32 v22, v0
	v_mov_b32_e32 v23, v0
	v_mov_b32_e32 v32, v0
	v_mov_b32_e32 v33, v0
	v_mov_b32_e32 v34, v0
	s_waitcnt lgkmcnt(0)
	v_mov_b32_e32 v35, v0
	v_mov_b32_e32 v36, v0
	v_mov_b32_e32 v37, v0
	v_mov_b32_e32 v38, v0
	v_mov_b32_e32 v39, v0
	v_mov_b32_e32 v48, v0
	v_mov_b32_e32 v49, v0
	v_mov_b32_e32 v50, v0
	v_mov_b32_e32 v51, v0
	v_mov_b32_e32 v52, v0
	v_mov_b32_e32 v53, v0
	v_mov_b32_e32 v54, v0
	v_mov_b32_e32 v55, v0
	v_mov_b32_e32 v56, v0
	v_mov_b32_e32 v57, v0
	v_mov_b32_e32 v58, v0
	v_mov_b32_e32 v59, v0
	v_mov_b32_e32 v60, v0
	v_mov_b32_e32 v61, v0
	v_mov_b32_e32 v62, v0
	v_mov_b32_e32 v63, v0
	v_mov_b32_e32 v64, v0
	v_mov_b32_e32 v65, v0
	v_mov_b32_e32 v66, v0
	v_mov_b32_e32 v67, v0
	v_mov_b32_e32 v68, v0
	v_mov_b32_e32 v69, v0
	v_mov_b32_e32 v70, v0
	v_mov_b32_e32 v71, v0
	v_mov_b32_e32 v72, v0
	v_mov_b32_e32 v73, v0
	v_mov_b32_e32 v74, v0
	v_mov_b32_e32 v75, v0
	v_mov_b32_e32 v76, v0
	v_mov_b32_e32 v77, v0
	v_mov_b32_e32 v78, v0
	v_mov_b32_e32 v79, v0
	v_mov_b32_e32 v88, v0
	v_mov_b32_e32 v89, v0
	v_mov_b32_e32 v90, v0
	v_mov_b32_e32 v91, v0
	v_mov_b32_e32 v92, v0
	v_mov_b32_e32 v93, v0
	v_mov_b32_e32 v94, v0
	v_mov_b32_e32 v95, v0
	v_mov_b32_e32 v104, v0
	v_mov_b32_e32 v105, v0
	v_mov_b32_e32 v106, v0
	v_mov_b32_e32 v107, v0
	v_mov_b32_e32 v112, v0
	v_mov_b32_e32 v113, v0
	v_mov_b32_e32 v114, v0
	v_mov_b32_e32 v115, v0
	v_mov_b32_e32 v80, v0
	v_mov_b32_e32 v81, v0
	v_mov_b32_e32 v82, v0
	v_mov_b32_e32 v83, v0
	v_mov_b32_e32 v84, v0
	v_mov_b32_e32 v85, v0
	v_mov_b32_e32 v86, v0
	v_mov_b32_e32 v87, v0
	v_mov_b32_e32 v96, v0
	v_mov_b32_e32 v97, v0
	v_mov_b32_e32 v98, v0
	v_mov_b32_e32 v99, v0
	v_mov_b32_e32 v100, v0
	v_mov_b32_e32 v101, v0
	v_mov_b32_e32 v102, v0
	v_mov_b32_e32 v103, v0
	v_mov_b32_e32 v108, v0
	v_mov_b32_e32 v109, v0
	v_mov_b32_e32 v110, v0
	v_mov_b32_e32 v111, v0
	v_mov_b32_e32 v116, v0
	v_mov_b32_e32 v117, v0
	v_mov_b32_e32 v118, v0
	v_mov_b32_e32 v119, v0
	v_mov_b32_e32 v120, v0
	v_mov_b32_e32 v121, v0
	v_mov_b32_e32 v122, v0
	v_mov_b32_e32 v123, v0
	v_mov_b32_e32 v124, v0
	v_mov_b32_e32 v125, v0
	v_mov_b32_e32 v126, v0
	v_mov_b32_e32 v127, v0
	.p2align 6

.LBB0_536:
	s_ashr_i32 s23, s22, 31
	s_lshl_b64 s[24:25], s[22:23], 19
	s_add_u32 s24, s3, s24
	s_addc_u32 s25, s38, s25
	s_and_b64 s[26:27], s[6:7], exec
	s_cselect_b32 s23, s25, s31
	s_cselect_b32 s29, s24, s30
	s_ashr_i32 s21, s20, 31
	s_lshl_b64 s[26:27], s[20:21], 19
	s_add_u32 s26, s39, s26
	s_addc_u32 s27, s40, s27
	s_and_b64 s[36:37], s[6:7], exec
	s_cselect_b32 s21, s27, s35
	s_cselect_b32 s61, s26, s34
	s_add_u32 s30, s30, 0x40080
	s_addc_u32 s31, s31, 0
	s_add_u32 s62, s34, 0x100
	v_mov_b32_e32 v0, 0
	s_addc_u32 s63, s35, 0
	s_mov_b32 s64, -2
	s_waitcnt lgkmcnt(0)
	v_mov_b32_e32 v1, v0
	v_mov_b32_e32 v2, v0
	v_mov_b32_e32 v3, v0
	v_mov_b32_e32 v4, v0
	v_mov_b32_e32 v5, v0
	v_mov_b32_e32 v6, v0
	v_mov_b32_e32 v7, v0
	v_mov_b32_e32 v16, v0
	v_mov_b32_e32 v17, v0
	v_mov_b32_e32 v18, v0
	v_mov_b32_e32 v19, v0
	v_mov_b32_e32 v20, v0
	v_mov_b32_e32 v21, v0
	v_mov_b32_e32 v22, v0
	v_mov_b32_e32 v23, v0
	v_mov_b32_e32 v32, v0
	v_mov_b32_e32 v33, v0
	v_mov_b32_e32 v34, v0
	s_waitcnt lgkmcnt(0)
	v_mov_b32_e32 v35, v0
	v_mov_b32_e32 v36, v0
	v_mov_b32_e32 v37, v0
	v_mov_b32_e32 v38, v0
	v_mov_b32_e32 v39, v0
	v_mov_b32_e32 v48, v0
	v_mov_b32_e32 v49, v0
	v_mov_b32_e32 v50, v0
	v_mov_b32_e32 v51, v0
	v_mov_b32_e32 v52, v0
	v_mov_b32_e32 v53, v0
	v_mov_b32_e32 v54, v0
	v_mov_b32_e32 v55, v0
	v_mov_b32_e32 v8, v0
	v_mov_b32_e32 v9, v0
	v_mov_b32_e32 v10, v0
	v_mov_b32_e32 v11, v0
	v_mov_b32_e32 v12, v0
	v_mov_b32_e32 v13, v0
	v_mov_b32_e32 v14, v0
	v_mov_b32_e32 v15, v0
	v_mov_b32_e32 v24, v0
	v_mov_b32_e32 v25, v0
	v_mov_b32_e32 v26, v0
	v_mov_b32_e32 v27, v0
	v_mov_b32_e32 v28, v0
	v_mov_b32_e32 v29, v0
	v_mov_b32_e32 v30, v0
	v_mov_b32_e32 v31, v0
	v_mov_b32_e32 v40, v0
	v_mov_b32_e32 v41, v0
	v_mov_b32_e32 v42, v0
	v_mov_b32_e32 v43, v0
	v_mov_b32_e32 v44, v0
	v_mov_b32_e32 v45, v0
	v_mov_b32_e32 v46, v0
	v_mov_b32_e32 v47, v0
	v_mov_b32_e32 v56, v0
	v_mov_b32_e32 v57, v0
	v_mov_b32_e32 v58, v0
	v_mov_b32_e32 v59, v0
	v_mov_b32_e32 v60, v0
	v_mov_b32_e32 v61, v0
	v_mov_b32_e32 v62, v0
	v_mov_b32_e32 v63, v0
	v_mov_b32_e32 v64, v0
	v_mov_b32_e32 v65, v0
	v_mov_b32_e32 v66, v0
	v_mov_b32_e32 v67, v0
	v_mov_b32_e32 v68, v0
	v_mov_b32_e32 v69, v0
	v_mov_b32_e32 v70, v0
	v_mov_b32_e32 v71, v0
	v_mov_b32_e32 v80, v0
	v_mov_b32_e32 v81, v0
	v_mov_b32_e32 v82, v0
	v_mov_b32_e32 v83, v0
	v_mov_b32_e32 v84, v0
	v_mov_b32_e32 v85, v0
	v_mov_b32_e32 v86, v0
	v_mov_b32_e32 v87, v0
	v_mov_b32_e32 v96, v0
	v_mov_b32_e32 v97, v0
	v_mov_b32_e32 v98, v0
	v_mov_b32_e32 v99, v0
	v_mov_b32_e32 v100, v0
	v_mov_b32_e32 v101, v0
	v_mov_b32_e32 v102, v0
	v_mov_b32_e32 v103, v0
	v_mov_b32_e32 v112, v0
	v_mov_b32_e32 v113, v0
	v_mov_b32_e32 v114, v0
	v_mov_b32_e32 v115, v0
	s_waitcnt vmcnt(0)
	v_mov_b32_e32 v116, v0
	v_mov_b32_e32 v117, v0
	v_mov_b32_e32 v118, v0
	v_mov_b32_e32 v119, v0
	v_mov_b32_e32 v72, v0
	v_mov_b32_e32 v73, v0
	v_mov_b32_e32 v74, v0
	v_mov_b32_e32 v75, v0
	v_mov_b32_e32 v76, v0
	v_mov_b32_e32 v77, v0
	v_mov_b32_e32 v78, v0
	v_mov_b32_e32 v79, v0
	v_mov_b32_e32 v88, v0
	v_mov_b32_e32 v89, v0
	v_mov_b32_e32 v90, v0
	v_mov_b32_e32 v91, v0
	v_mov_b32_e32 v92, v0
	v_mov_b32_e32 v93, v0
	v_mov_b32_e32 v94, v0
	v_mov_b32_e32 v95, v0
	v_mov_b32_e32 v104, v0
	v_mov_b32_e32 v105, v0
	v_mov_b32_e32 v106, v0
	v_mov_b32_e32 v107, v0
	v_mov_b32_e32 v108, v0
	v_mov_b32_e32 v109, v0
	v_mov_b32_e32 v110, v0
	v_mov_b32_e32 v111, v0
	v_mov_b32_e32 v120, v0
	v_mov_b32_e32 v121, v0
	v_mov_b32_e32 v122, v0
	v_mov_b32_e32 v123, v0
	v_mov_b32_e32 v124, v0
	v_mov_b32_e32 v125, v0
	v_mov_b32_e32 v126, v0
	v_mov_b32_e32 v127, v0
	.p2align 6

.LBB0_623:
	s_ashr_i32 s19, s18, 31
	s_lshl_b64 s[20:21], s[18:19], 19
	s_add_u32 s20, s3, s20
	s_addc_u32 s21, s30, s21
	s_and_b64 s[22:23], s[4:5], exec
	s_cselect_b32 s19, s21, s25
	s_cselect_b32 s53, s20, s24
	s_ashr_i32 s17, s16, 31
	s_lshl_b64 s[22:23], s[16:17], 19
	s_add_u32 s22, s31, s22
	s_addc_u32 s23, s34, s23
	s_and_b64 s[28:29], s[4:5], exec
	s_cselect_b32 s17, s23, s27
	s_cselect_b32 s54, s22, s26
	s_add_u32 s24, s24, 0x40080
	s_addc_u32 s25, s25, 0
	s_add_u32 s55, s26, 0x100
	v_mov_b32_e32 v8, 0
	s_addc_u32 s56, s27, 0
	s_mov_b32 s57, -2
	v_mov_b32_e32 v9, v8
	v_mov_b32_e32 v10, v8
	v_mov_b32_e32 v11, v8
	v_mov_b32_e32 v12, v8
	v_mov_b32_e32 v13, v8
	v_mov_b32_e32 v14, v8
	v_mov_b32_e32 v15, v8
	v_mov_b32_e32 v24, v8
	v_mov_b32_e32 v25, v8
	v_mov_b32_e32 v26, v8
	v_mov_b32_e32 v27, v8
	v_mov_b32_e32 v28, v8
	v_mov_b32_e32 v29, v8
	v_mov_b32_e32 v30, v8
	v_mov_b32_e32 v31, v8
	v_mov_b32_e32 v40, v8
	v_mov_b32_e32 v41, v8
	v_mov_b32_e32 v42, v8
	v_mov_b32_e32 v43, v8
	v_mov_b32_e32 v44, v8
	v_mov_b32_e32 v45, v8
	v_mov_b32_e32 v46, v8
	v_mov_b32_e32 v47, v8
	v_mov_b32_e32 v56, v8
	v_mov_b32_e32 v57, v8
	v_mov_b32_e32 v58, v8
	v_mov_b32_e32 v59, v8
	v_mov_b32_e32 v60, v8
	v_mov_b32_e32 v61, v8
	v_mov_b32_e32 v62, v8
	v_mov_b32_e32 v63, v8
	v_mov_b32_e32 v0, v8
	v_mov_b32_e32 v1, v8
	v_mov_b32_e32 v2, v8
	v_mov_b32_e32 v3, v8
	v_mov_b32_e32 v4, v8
	v_mov_b32_e32 v5, v8
	v_mov_b32_e32 v6, v8
	v_mov_b32_e32 v7, v8
	v_mov_b32_e32 v16, v8
	v_mov_b32_e32 v17, v8
	v_mov_b32_e32 v18, v8
	v_mov_b32_e32 v19, v8
	v_mov_b32_e32 v20, v8
	v_mov_b32_e32 v21, v8
	v_mov_b32_e32 v22, v8
	v_mov_b32_e32 v23, v8
	v_mov_b32_e32 v32, v8
	v_mov_b32_e32 v33, v8
	v_mov_b32_e32 v34, v8
	v_mov_b32_e32 v35, v8
	v_mov_b32_e32 v36, v8
	v_mov_b32_e32 v37, v8
	v_mov_b32_e32 v38, v8
	v_mov_b32_e32 v39, v8
	v_mov_b32_e32 v48, v8
	v_mov_b32_e32 v49, v8
	v_mov_b32_e32 v50, v8
	v_mov_b32_e32 v51, v8
	v_mov_b32_e32 v52, v8
	v_mov_b32_e32 v53, v8
	v_mov_b32_e32 v54, v8
	v_mov_b32_e32 v55, v8
	v_mov_b32_e32 v72, v8
	v_mov_b32_e32 v73, v8
	v_mov_b32_e32 v74, v8
	v_mov_b32_e32 v75, v8
	v_mov_b32_e32 v76, v8
	v_mov_b32_e32 v77, v8
	v_mov_b32_e32 v78, v8
	v_mov_b32_e32 v79, v8
	v_mov_b32_e32 v88, v8
	v_mov_b32_e32 v89, v8
	v_mov_b32_e32 v90, v8
	v_mov_b32_e32 v91, v8
	v_mov_b32_e32 v92, v8
	v_mov_b32_e32 v93, v8
	v_mov_b32_e32 v94, v8
	v_mov_b32_e32 v95, v8
	v_mov_b32_e32 v104, v8
	v_mov_b32_e32 v105, v8
	v_mov_b32_e32 v106, v8
	v_mov_b32_e32 v107, v8
	v_mov_b32_e32 v108, v8
	v_mov_b32_e32 v109, v8
	v_mov_b32_e32 v110, v8
	v_mov_b32_e32 v111, v8
	v_mov_b32_e32 v120, v8
	v_mov_b32_e32 v121, v8
	v_mov_b32_e32 v122, v8
	v_mov_b32_e32 v123, v8
	v_mov_b32_e32 v124, v8
	v_mov_b32_e32 v125, v8
	v_mov_b32_e32 v126, v8
	v_mov_b32_e32 v127, v8
	v_mov_b32_e32 v64, v8
	v_mov_b32_e32 v65, v8
	v_mov_b32_e32 v66, v8
	v_mov_b32_e32 v67, v8
	v_mov_b32_e32 v68, v8
	v_mov_b32_e32 v69, v8
	v_mov_b32_e32 v70, v8
	v_mov_b32_e32 v71, v8
	v_mov_b32_e32 v80, v8
	v_mov_b32_e32 v81, v8
	v_mov_b32_e32 v82, v8
	v_mov_b32_e32 v83, v8
	v_mov_b32_e32 v84, v8
	v_mov_b32_e32 v85, v8
	v_mov_b32_e32 v86, v8
	v_mov_b32_e32 v87, v8
	v_mov_b32_e32 v96, v8
	v_mov_b32_e32 v97, v8
	v_mov_b32_e32 v98, v8
	v_mov_b32_e32 v99, v8
	v_mov_b32_e32 v100, v8
	v_mov_b32_e32 v101, v8
	v_mov_b32_e32 v102, v8
	v_mov_b32_e32 v103, v8
	v_mov_b32_e32 v112, v8
	v_mov_b32_e32 v113, v8
	v_mov_b32_e32 v114, v8
	v_mov_b32_e32 v115, v8
	s_waitcnt vmcnt(0)
	v_mov_b32_e32 v116, v8
	v_mov_b32_e32 v117, v8
	v_mov_b32_e32 v118, v8
	v_mov_b32_e32 v119, v8
	.p2align 6

.LBB0_708:
	s_add_u32 s24, s24, 0xb0080
	s_addc_u32 s25, s25, 0
	s_add_u32 s54, s26, 0x100
	v_mov_b32_e32 v0, 0
	s_addc_u32 s55, s27, 0
	s_mov_b32 s56, -2
	s_waitcnt lgkmcnt(0)
	v_mov_b32_e32 v1, v0
	v_mov_b32_e32 v2, v0
	v_mov_b32_e32 v3, v0
	v_mov_b32_e32 v4, v0
	v_mov_b32_e32 v5, v0
	v_mov_b32_e32 v6, v0
	v_mov_b32_e32 v7, v0
	v_mov_b32_e32 v16, v0
	v_mov_b32_e32 v17, v0
	v_mov_b32_e32 v18, v0
	v_mov_b32_e32 v19, v0
	v_mov_b32_e32 v20, v0
	v_mov_b32_e32 v21, v0
	v_mov_b32_e32 v22, v0
	v_mov_b32_e32 v23, v0
	v_mov_b32_e32 v32, v0
	v_mov_b32_e32 v33, v0
	v_mov_b32_e32 v34, v0
	v_mov_b32_e32 v35, v0
	v_mov_b32_e32 v36, v0
	v_mov_b32_e32 v37, v0
	v_mov_b32_e32 v38, v0
	v_mov_b32_e32 v39, v0
	v_mov_b32_e32 v48, v0
	v_mov_b32_e32 v49, v0
	v_mov_b32_e32 v50, v0
	v_mov_b32_e32 v51, v0
	v_mov_b32_e32 v52, v0
	v_mov_b32_e32 v53, v0
	v_mov_b32_e32 v54, v0
	v_mov_b32_e32 v55, v0
	v_mov_b32_e32 v8, v0
	v_mov_b32_e32 v9, v0
	v_mov_b32_e32 v10, v0
	v_mov_b32_e32 v11, v0
	v_mov_b32_e32 v12, v0
	v_mov_b32_e32 v13, v0
	v_mov_b32_e32 v14, v0
	v_mov_b32_e32 v15, v0
	v_mov_b32_e32 v24, v0
	v_mov_b32_e32 v25, v0
	v_mov_b32_e32 v26, v0
	v_mov_b32_e32 v27, v0
	v_mov_b32_e32 v28, v0
	v_mov_b32_e32 v29, v0
	v_mov_b32_e32 v30, v0
	v_mov_b32_e32 v31, v0
	v_mov_b32_e32 v40, v0
	v_mov_b32_e32 v41, v0
	v_mov_b32_e32 v42, v0
	v_mov_b32_e32 v43, v0
	v_mov_b32_e32 v44, v0
	v_mov_b32_e32 v45, v0
	v_mov_b32_e32 v46, v0
	v_mov_b32_e32 v47, v0
	v_mov_b32_e32 v56, v0
	v_mov_b32_e32 v57, v0
	v_mov_b32_e32 v58, v0
	v_mov_b32_e32 v59, v0
	v_mov_b32_e32 v60, v0
	v_mov_b32_e32 v61, v0
	v_mov_b32_e32 v62, v0
	v_mov_b32_e32 v63, v0
	v_mov_b32_e32 v64, v0
	v_mov_b32_e32 v65, v0
	v_mov_b32_e32 v66, v0
	v_mov_b32_e32 v67, v0
	v_mov_b32_e32 v68, v0
	v_mov_b32_e32 v69, v0
	v_mov_b32_e32 v70, v0
	v_mov_b32_e32 v71, v0
	v_mov_b32_e32 v80, v0
	v_mov_b32_e32 v81, v0
	v_mov_b32_e32 v82, v0
	v_mov_b32_e32 v83, v0
	v_mov_b32_e32 v84, v0
	v_mov_b32_e32 v85, v0
	v_mov_b32_e32 v86, v0
	v_mov_b32_e32 v87, v0
	v_mov_b32_e32 v96, v0
	v_mov_b32_e32 v97, v0
	v_mov_b32_e32 v98, v0
	v_mov_b32_e32 v99, v0
	v_mov_b32_e32 v100, v0
	v_mov_b32_e32 v101, v0
	v_mov_b32_e32 v102, v0
	v_mov_b32_e32 v103, v0
	v_mov_b32_e32 v112, v0
	v_mov_b32_e32 v113, v0
	v_mov_b32_e32 v114, v0
	v_mov_b32_e32 v115, v0
	s_waitcnt vmcnt(0)
	v_mov_b32_e32 v116, v0
	v_mov_b32_e32 v117, v0
	v_mov_b32_e32 v118, v0
	v_mov_b32_e32 v119, v0
	v_mov_b32_e32 v72, v0
	v_mov_b32_e32 v73, v0
	v_mov_b32_e32 v74, v0
	v_mov_b32_e32 v75, v0
	v_mov_b32_e32 v76, v0
	v_mov_b32_e32 v77, v0
	v_mov_b32_e32 v78, v0
	v_mov_b32_e32 v79, v0
	v_mov_b32_e32 v88, v0
	v_mov_b32_e32 v89, v0
	v_mov_b32_e32 v90, v0
	v_mov_b32_e32 v91, v0
	v_mov_b32_e32 v92, v0
	v_mov_b32_e32 v93, v0
	v_mov_b32_e32 v94, v0
	v_mov_b32_e32 v95, v0
	v_mov_b32_e32 v104, v0
	v_mov_b32_e32 v105, v0
	v_mov_b32_e32 v106, v0
	v_mov_b32_e32 v107, v0
	v_mov_b32_e32 v108, v0
	v_mov_b32_e32 v109, v0
	v_mov_b32_e32 v110, v0
	v_mov_b32_e32 v111, v0
	v_mov_b32_e32 v120, v0
	v_mov_b32_e32 v121, v0
	v_mov_b32_e32 v122, v0
	v_mov_b32_e32 v123, v0
	v_mov_b32_e32 v124, v0
	v_mov_b32_e32 v125, v0
	v_mov_b32_e32 v126, v0
	v_mov_b32_e32 v127, v0
	.p2align 6

.LBB0_805:
	s_ashr_i32 s21, s20, 31
	s_lshl_b64 s[22:23], s[20:21], 19
	s_add_u32 s22, s3, s22
	s_addc_u32 s23, s34, s23
	s_and_b64 s[24:25], s[4:5], exec
	s_cselect_b32 s1, s23, s27
	s_cselect_b32 s7, s22, s26
	s_ashr_i32 s19, s18, 31
	s_lshl_b64 s[24:25], s[18:19], 19
	s_add_u32 s24, s35, s24
	s_addc_u32 s25, s36, s25
	s_and_b64 s[30:31], s[4:5], exec
	s_cselect_b32 s19, s25, s29
	s_cselect_b32 s21, s24, s28
	s_add_u32 s26, s26, 0x40080
	s_addc_u32 s27, s27, 0
	s_add_u32 s54, s28, 0x100
	v_mov_b32_e32 v0, 0
	s_addc_u32 s55, s29, 0
	s_mov_b32 s56, -2
	v_mov_b32_e32 v1, v0
	v_mov_b32_e32 v2, v0
	v_mov_b32_e32 v3, v0
	v_mov_b32_e32 v4, v0
	v_mov_b32_e32 v5, v0
	v_mov_b32_e32 v6, v0
	v_mov_b32_e32 v7, v0
	v_mov_b32_e32 v16, v0
	v_mov_b32_e32 v17, v0
	v_mov_b32_e32 v18, v0
	v_mov_b32_e32 v19, v0
	v_mov_b32_e32 v20, v0
	v_mov_b32_e32 v21, v0
	v_mov_b32_e32 v22, v0
	v_mov_b32_e32 v23, v0
	v_mov_b32_e32 v32, v0
	v_mov_b32_e32 v33, v0
	v_mov_b32_e32 v34, v0
	v_mov_b32_e32 v35, v0
	v_mov_b32_e32 v36, v0
	v_mov_b32_e32 v37, v0
	v_mov_b32_e32 v38, v0
	v_mov_b32_e32 v39, v0
	v_mov_b32_e32 v48, v0
	v_mov_b32_e32 v49, v0
	v_mov_b32_e32 v50, v0
	v_mov_b32_e32 v51, v0
	v_mov_b32_e32 v52, v0
	v_mov_b32_e32 v53, v0
	v_mov_b32_e32 v54, v0
	v_mov_b32_e32 v55, v0
	v_mov_b32_e32 v8, v0
	v_mov_b32_e32 v9, v0
	v_mov_b32_e32 v10, v0
	v_mov_b32_e32 v11, v0
	v_mov_b32_e32 v12, v0
	v_mov_b32_e32 v13, v0
	v_mov_b32_e32 v14, v0
	v_mov_b32_e32 v15, v0
	v_mov_b32_e32 v24, v0
	v_mov_b32_e32 v25, v0
	v_mov_b32_e32 v26, v0
	v_mov_b32_e32 v27, v0
	v_mov_b32_e32 v28, v0
	v_mov_b32_e32 v29, v0
	v_mov_b32_e32 v30, v0
	v_mov_b32_e32 v31, v0
	v_mov_b32_e32 v40, v0
	v_mov_b32_e32 v41, v0
	v_mov_b32_e32 v42, v0
	v_mov_b32_e32 v43, v0
	v_mov_b32_e32 v44, v0
	v_mov_b32_e32 v45, v0
	v_mov_b32_e32 v46, v0
	v_mov_b32_e32 v47, v0
	v_mov_b32_e32 v56, v0
	v_mov_b32_e32 v57, v0
	v_mov_b32_e32 v58, v0
	v_mov_b32_e32 v59, v0
	v_mov_b32_e32 v60, v0
	v_mov_b32_e32 v61, v0
	v_mov_b32_e32 v62, v0
	v_mov_b32_e32 v63, v0
	v_mov_b32_e32 v64, v0
	v_mov_b32_e32 v65, v0
	v_mov_b32_e32 v66, v0
	v_mov_b32_e32 v67, v0
	v_mov_b32_e32 v68, v0
	v_mov_b32_e32 v69, v0
	v_mov_b32_e32 v70, v0
	v_mov_b32_e32 v71, v0
	v_mov_b32_e32 v80, v0
	v_mov_b32_e32 v81, v0
	v_mov_b32_e32 v82, v0
	v_mov_b32_e32 v83, v0
	v_mov_b32_e32 v84, v0
	v_mov_b32_e32 v85, v0
	v_mov_b32_e32 v86, v0
	v_mov_b32_e32 v87, v0
	v_mov_b32_e32 v96, v0
	v_mov_b32_e32 v97, v0
	v_mov_b32_e32 v98, v0
	v_mov_b32_e32 v99, v0
	v_mov_b32_e32 v100, v0
	v_mov_b32_e32 v101, v0
	v_mov_b32_e32 v102, v0
	v_mov_b32_e32 v103, v0
	v_mov_b32_e32 v112, v0
	v_mov_b32_e32 v113, v0
	v_mov_b32_e32 v114, v0
	v_mov_b32_e32 v115, v0
	s_waitcnt vmcnt(0)
	v_mov_b32_e32 v116, v0
	v_mov_b32_e32 v117, v0
	v_mov_b32_e32 v118, v0
	v_mov_b32_e32 v119, v0
	v_mov_b32_e32 v72, v0
	v_mov_b32_e32 v73, v0
	v_mov_b32_e32 v74, v0
	v_mov_b32_e32 v75, v0
	v_mov_b32_e32 v76, v0
	v_mov_b32_e32 v77, v0
	v_mov_b32_e32 v78, v0
	v_mov_b32_e32 v79, v0
	v_mov_b32_e32 v88, v0
	v_mov_b32_e32 v89, v0
	v_mov_b32_e32 v90, v0
	v_mov_b32_e32 v91, v0
	v_mov_b32_e32 v92, v0
	v_mov_b32_e32 v93, v0
	v_mov_b32_e32 v94, v0
	v_mov_b32_e32 v95, v0
	v_mov_b32_e32 v104, v0
	v_mov_b32_e32 v105, v0
	v_mov_b32_e32 v106, v0
	v_mov_b32_e32 v107, v0
	v_mov_b32_e32 v108, v0
	v_mov_b32_e32 v109, v0
	v_mov_b32_e32 v110, v0
	v_mov_b32_e32 v111, v0
	v_mov_b32_e32 v120, v0
	v_mov_b32_e32 v121, v0
	v_mov_b32_e32 v122, v0
	v_mov_b32_e32 v123, v0
	v_mov_b32_e32 v124, v0
	v_mov_b32_e32 v125, v0
	v_mov_b32_e32 v126, v0
	v_mov_b32_e32 v127, v0
	.p2align 6

.LBB0_1147:
	s_ashr_i32 s23, s22, 31
	s_lshl_b64 s[24:25], s[22:23], 19
	s_add_u32 s24, s3, s24
	s_addc_u32 s25, s38, s25
	s_and_b64 s[26:27], s[6:7], exec
	s_cselect_b32 s23, s25, s31
	s_cselect_b32 s29, s24, s30
	s_ashr_i32 s21, s20, 31
	s_lshl_b64 s[26:27], s[20:21], 19
	s_add_u32 s26, s39, s26
	s_addc_u32 s27, s40, s27
	s_and_b64 s[36:37], s[6:7], exec
	s_cselect_b32 s21, s27, s35
	s_cselect_b32 s57, s26, s34
	s_add_u32 s30, s30, 0x40080
	s_addc_u32 s31, s31, 0
	s_add_u32 s60, s34, 0x100
	v_mov_b32_e32 v0, 0
	s_addc_u32 s61, s35, 0
	s_mov_b32 s62, -2
	s_waitcnt lgkmcnt(0)
	v_mov_b32_e32 v1, v0
	v_mov_b32_e32 v2, v0
	v_mov_b32_e32 v3, v0
	v_mov_b32_e32 v4, v0
	v_mov_b32_e32 v5, v0
	v_mov_b32_e32 v6, v0
	v_mov_b32_e32 v7, v0
	v_mov_b32_e32 v16, v0
	v_mov_b32_e32 v17, v0
	v_mov_b32_e32 v18, v0
	v_mov_b32_e32 v19, v0
	v_mov_b32_e32 v20, v0
	v_mov_b32_e32 v21, v0
	v_mov_b32_e32 v22, v0
	v_mov_b32_e32 v23, v0
	v_mov_b32_e32 v32, v0
	v_mov_b32_e32 v33, v0
	v_mov_b32_e32 v34, v0
	v_mov_b32_e32 v35, v0
	v_mov_b32_e32 v36, v0
	v_mov_b32_e32 v37, v0
	v_mov_b32_e32 v38, v0
	v_mov_b32_e32 v39, v0
	v_mov_b32_e32 v48, v0
	v_mov_b32_e32 v49, v0
	v_mov_b32_e32 v50, v0
	v_mov_b32_e32 v51, v0
	v_mov_b32_e32 v52, v0
	v_mov_b32_e32 v53, v0
	v_mov_b32_e32 v54, v0
	v_mov_b32_e32 v55, v0
	v_mov_b32_e32 v8, v0
	v_mov_b32_e32 v9, v0
	v_mov_b32_e32 v10, v0
	v_mov_b32_e32 v11, v0
	v_mov_b32_e32 v12, v0
	v_mov_b32_e32 v13, v0
	v_mov_b32_e32 v14, v0
	v_mov_b32_e32 v15, v0
	v_mov_b32_e32 v24, v0
	v_mov_b32_e32 v25, v0
	v_mov_b32_e32 v26, v0
	v_mov_b32_e32 v27, v0
	v_mov_b32_e32 v28, v0
	v_mov_b32_e32 v29, v0
	v_mov_b32_e32 v30, v0
	v_mov_b32_e32 v31, v0
	v_mov_b32_e32 v40, v0
	v_mov_b32_e32 v41, v0
	v_mov_b32_e32 v42, v0
	v_mov_b32_e32 v43, v0
	v_mov_b32_e32 v44, v0
	v_mov_b32_e32 v45, v0
	v_mov_b32_e32 v46, v0
	v_mov_b32_e32 v47, v0
	v_mov_b32_e32 v56, v0
	v_mov_b32_e32 v57, v0
	v_mov_b32_e32 v58, v0
	v_mov_b32_e32 v59, v0
	v_mov_b32_e32 v60, v0
	v_mov_b32_e32 v61, v0
	v_mov_b32_e32 v62, v0
	v_mov_b32_e32 v63, v0
	v_mov_b32_e32 v64, v0
	v_mov_b32_e32 v65, v0
	v_mov_b32_e32 v66, v0
	v_mov_b32_e32 v67, v0
	v_mov_b32_e32 v68, v0
	v_mov_b32_e32 v69, v0
	v_mov_b32_e32 v70, v0
	v_mov_b32_e32 v71, v0
	v_mov_b32_e32 v80, v0
	v_mov_b32_e32 v81, v0
	v_mov_b32_e32 v82, v0
	v_mov_b32_e32 v83, v0
	v_mov_b32_e32 v84, v0
	v_mov_b32_e32 v85, v0
	v_mov_b32_e32 v86, v0
	v_mov_b32_e32 v87, v0
	v_mov_b32_e32 v96, v0
	v_mov_b32_e32 v97, v0
	v_mov_b32_e32 v98, v0
	v_mov_b32_e32 v99, v0
	v_mov_b32_e32 v100, v0
	v_mov_b32_e32 v101, v0
	v_mov_b32_e32 v102, v0
	v_mov_b32_e32 v103, v0
	v_mov_b32_e32 v112, v0
	v_mov_b32_e32 v113, v0
	v_mov_b32_e32 v114, v0
	v_mov_b32_e32 v115, v0
	s_waitcnt vmcnt(0)
	v_mov_b32_e32 v116, v0
	v_mov_b32_e32 v117, v0
	v_mov_b32_e32 v118, v0
	v_mov_b32_e32 v119, v0
	v_mov_b32_e32 v72, v0
	v_mov_b32_e32 v73, v0
	v_mov_b32_e32 v74, v0
	v_mov_b32_e32 v75, v0
	v_mov_b32_e32 v76, v0
	v_mov_b32_e32 v77, v0
	v_mov_b32_e32 v78, v0
	v_mov_b32_e32 v79, v0
	v_mov_b32_e32 v88, v0
	v_mov_b32_e32 v89, v0
	v_mov_b32_e32 v90, v0
	v_mov_b32_e32 v91, v0
	v_mov_b32_e32 v92, v0
	v_mov_b32_e32 v93, v0
	v_mov_b32_e32 v94, v0
	v_mov_b32_e32 v95, v0
	v_mov_b32_e32 v104, v0
	v_mov_b32_e32 v105, v0
	v_mov_b32_e32 v106, v0
	v_mov_b32_e32 v107, v0
	v_mov_b32_e32 v108, v0
	v_mov_b32_e32 v109, v0
	v_mov_b32_e32 v110, v0
	v_mov_b32_e32 v111, v0
	v_mov_b32_e32 v120, v0
	v_mov_b32_e32 v121, v0
	v_mov_b32_e32 v122, v0
	v_mov_b32_e32 v123, v0
	v_mov_b32_e32 v124, v0
	v_mov_b32_e32 v125, v0
	v_mov_b32_e32 v126, v0
	v_mov_b32_e32 v127, v0
	.p2align 6
